# hyena forward FFT passes with stride >= 16: leg addresses A0+k*S via 3 adds (second loop copy) instead of re-deriving the padded address per leg
# speedup vs baseline: 1.0035x; 1.0008x over previous
; DI float sin_t(float turns) { return __builtin_amdgcn_sinf(__builtin_amdgcn_fractf(turns)); }
; DI float cos_t(float turns) { return __builtin_amdgcn_cosf(__builtin_amdgcn_fractf(turns)); }
; DI float2 cmul(float2 a, float2 b) { return make_float2(a.x * b.x - a.y * b.y, a.x * b.y + a.y * b.x); }
; template <int N, bool INV>
; DI void fft_lds(float2* s) {
;     ...
;     for (int lq = (LG & 1) ? LG - 3 : LG - 2; lq >= 0; lq -= 2) {
;       const int q = 1 << lq;
;       __syncthreads();
;       const float inv4q = 1.0f / (float)(4 * q);
; #pragma unroll 4
;       for (int it = 0; it < N / 4 / NT; ++it) {
;         int idx = tid + it * NT;
;         int j = idx & (q - 1), blk = idx >> lq;
;         int p0 = blk * 4 * q + j;
;         float f = (float)j * inv4q;
;         float2 t1 = make_float2(cos_t(f), -sin_t(f));
;         float2 t2 = cmul(t1, t1);
;         float2 x0 = s[phys(p0)], x1 = s[phys(p0 + q)], x2 = s[phys(p0 + 2 * q)], x3 = s[phys(p0 + 3 * q)];
;         float2 a0 = make_float2(x0.x + x2.x, x0.y + x2.y);
;         float2 a2 = cmul(make_float2(x0.x - x2.x, x0.y - x2.y), t1);
;         float2 a1 = make_float2(x1.x + x3.x, x1.y + x3.y);
;         float2 d3 = make_float2(x1.x - x3.x, x1.y - x3.y);
;         float2 a3 = cmul(make_float2(d3.y, -d3.x), t1);
;         s[phys(p0)] = make_float2(a0.x + a1.x, a0.y + a1.y);
;         s[phys(p0 + q)] = cmul(make_float2(a0.x - a1.x, a0.y - a1.y), t2);
;         s[phys(p0 + 2 * q)] = make_float2(a2.x + a3.x, a2.y + a3.y);
;         s[phys(p0 + 3 * q)] = cmul(make_float2(a2.x - a3.x, a2.y - a3.y), t2);
;       }
.LBB0_472:
	s_lshl_b32 s1, 4, s0
	v_cvt_f32_u32_e32 v2, s1
	s_lshl_b32 s1, 1, s0
	s_waitcnt lgkmcnt(0)
	s_barrier
	v_div_scale_f32 v3, s[4:5], v2, v2, 1.0
	v_rcp_f32_e32 v4, v3
	s_bfm_b32 s4, s0, 0
	s_mov_b32 s5, 0
	v_fma_f32 v5, -v3, v4, 1.0
	v_fmac_f32_e32 v4, v5, v4
	v_div_scale_f32 v5, vcc, 1.0, v2, 1.0
	v_mul_f32_e32 v6, v5, v4
	v_fma_f32 v7, -v3, v6, v5
	v_fmac_f32_e32 v6, v7, v4
	v_fma_f32 v3, -v3, v6, v5
	v_div_fmas_f32 v3, v3, v4, v6
	v_div_fixup_f32 v2, v3, v2, 1.0
	s_sub_i32 s32, s0, 4
	s_lshl_b32 s32, 0x88, s32
	s_cmp_lt_u32 s0, 4
	s_cbranch_scc0 .Lfft_fast_0
.LBB0_473:
	v_add_u32_e32 v3, s5, v1
	v_ashrrev_i32_e32 v4, s0, v3
	v_and_b32_e32 v9, s4, v3
	v_lshlrev_b32_e32 v10, 2, v4
	v_lshl_add_u32 v11, v10, s0, v9
	v_ashrrev_i32_e32 v12, 4, v11
	v_add_lshl_u32 v21, v12, v11, 3
	v_add_u32_e32 v11, s1, v11
	v_cvt_f32_u32_e32 v4, v9
	v_ashrrev_i32_e32 v12, 4, v11
	v_add_lshl_u32 v26, v12, v11, 3
	v_or_b32_e32 v11, 2, v10
	v_or_b32_e32 v10, 3, v10
	v_lshl_add_u32 v11, v11, s0, v9
	v_lshl_add_u32 v9, v10, s0, v9
	v_mul_f32_e32 v4, v2, v4
	v_ashrrev_i32_e32 v12, 4, v11
	v_ashrrev_i32_e32 v10, 4, v9
	v_fract_f32_e32 v5, v4
	v_add_lshl_u32 v27, v12, v11, 3
	v_add_lshl_u32 v28, v10, v9, 3
	v_cos_f32_e32 v4, v5
	v_sin_f32_e32 v5, v5
	ds_read_b64 v[10:11], v21
	ds_read_b64 v[12:13], v26
	ds_read_b64 v[14:15], v27
	ds_read_b64 v[16:17], v28
	v_mov_b32_e32 v20, v5
	v_mul_f32_e64 v8, v4, -v5
	v_pk_mul_f32 v[6:7], v[4:5], v[4:5]
	s_waitcnt lgkmcnt(1)
	v_pk_add_f32 v[18:19], v[10:11], v[14:15] neg_lo:[0,1] neg_hi:[0,1]
	v_pk_add_f32 v[10:11], v[10:11], v[14:15]
	v_pk_mul_f32 v[22:23], v[20:21], v[18:19] op_sel_hi:[0,1]
	v_pk_fma_f32 v[24:25], v[18:19], v[4:5], v[22:23] op_sel:[0,0,1] op_sel_hi:[1,1,0]
	v_pk_fma_f32 v[18:19], v[18:19], v[4:5], v[22:23] op_sel:[0,0,1] op_sel_hi:[1,0,0] neg_lo:[0,0,1] neg_hi:[0,0,1]
	v_add_f32_e32 v8, v8, v8
	v_mov_b32_e32 v25, v19
	s_waitcnt lgkmcnt(0)
	v_pk_add_f32 v[18:19], v[12:13], v[16:17] neg_lo:[0,1] neg_hi:[0,1]
	v_pk_add_f32 v[12:13], v[12:13], v[16:17]
	v_xor_b32_e32 v23, 0x80000000, v18
	v_pk_add_f32 v[14:15], v[10:11], v[12:13]
	v_pk_add_f32 v[10:11], v[10:11], v[12:13] neg_lo:[0,1] neg_hi:[0,1]
	v_mov_b32_e32 v22, v19
	v_pk_mul_f32 v[18:19], v[20:21], v[18:19] op_sel_hi:[0,1]
	v_pk_mul_f32 v[12:13], v[8:9], v[10:11] op_sel_hi:[0,1]
	v_pk_add_f32 v[6:7], v[6:7], v[6:7] op_sel:[0,1] op_sel_hi:[0,1] neg_lo:[0,1] neg_hi:[0,1]
	v_pk_fma_f32 v[4:5], v[4:5], v[22:23], v[18:19] op_sel_hi:[0,1,1] neg_lo:[0,0,1] neg_hi:[0,0,1]
	ds_write_b64 v21, v[14:15]
	v_pk_fma_f32 v[14:15], v[6:7], v[10:11], v[12:13] op_sel:[0,0,1] op_sel_hi:[1,1,0] neg_lo:[0,0,1] neg_hi:[0,0,1]
	v_pk_fma_f32 v[10:11], v[6:7], v[10:11], v[12:13] op_sel:[0,0,1] op_sel_hi:[1,1,0]
	s_addk_i32 s5, 0x800
	v_mov_b32_e32 v15, v11
	v_pk_add_f32 v[10:11], v[24:25], v[4:5]
	v_pk_add_f32 v[4:5], v[24:25], v[4:5] neg_lo:[0,1] neg_hi:[0,1]
	ds_write_b64 v26, v[14:15]
	v_pk_mul_f32 v[8:9], v[8:9], v[4:5] op_sel_hi:[0,1]
	ds_write_b64 v27, v[10:11]
	v_pk_fma_f32 v[10:11], v[6:7], v[4:5], v[8:9] op_sel:[0,0,1] op_sel_hi:[1,1,0] neg_lo:[0,0,1] neg_hi:[0,0,1]
	v_pk_fma_f32 v[4:5], v[6:7], v[4:5], v[8:9] op_sel:[0,0,1] op_sel_hi:[1,1,0]
	s_cmpk_eq_i32 s5, 0x1000
	v_add_u32_e32 v4, 0x200, v3
	v_mov_b32_e32 v11, v5
	v_and_b32_e32 v9, s4, v4
	v_ashrrev_i32_e32 v4, s0, v4
	ds_write_b64 v28, v[10:11]
	v_lshlrev_b32_e32 v10, 2, v4
	v_lshl_add_u32 v11, v10, s0, v9
	v_ashrrev_i32_e32 v12, 4, v11
	v_add_lshl_u32 v21, v12, v11, 3
	v_add_u32_e32 v11, s1, v11
	v_cvt_f32_u32_e32 v4, v9
	v_ashrrev_i32_e32 v12, 4, v11
	v_add_lshl_u32 v26, v12, v11, 3
	v_or_b32_e32 v11, 2, v10
	v_or_b32_e32 v10, 3, v10
	v_lshl_add_u32 v11, v11, s0, v9
	v_lshl_add_u32 v9, v10, s0, v9
	v_mul_f32_e32 v4, v2, v4
	v_ashrrev_i32_e32 v12, 4, v11
	v_ashrrev_i32_e32 v10, 4, v9
	v_fract_f32_e32 v5, v4
	v_add_lshl_u32 v27, v12, v11, 3
	v_add_lshl_u32 v28, v10, v9, 3
	v_cos_f32_e32 v4, v5
	v_sin_f32_e32 v5, v5
	ds_read_b64 v[10:11], v21
	ds_read_b64 v[12:13], v26
	ds_read_b64 v[14:15], v27
	ds_read_b64 v[16:17], v28
	v_mov_b32_e32 v20, v5
	v_mul_f32_e64 v8, v4, -v5
	v_pk_mul_f32 v[6:7], v[4:5], v[4:5]
	s_waitcnt lgkmcnt(1)
	v_pk_add_f32 v[18:19], v[10:11], v[14:15] neg_lo:[0,1] neg_hi:[0,1]
	v_pk_add_f32 v[10:11], v[10:11], v[14:15]
	v_pk_mul_f32 v[22:23], v[20:21], v[18:19] op_sel_hi:[0,1]
	v_pk_fma_f32 v[24:25], v[18:19], v[4:5], v[22:23] op_sel:[0,0,1] op_sel_hi:[1,1,0]
	v_pk_fma_f32 v[18:19], v[18:19], v[4:5], v[22:23] op_sel:[0,0,1] op_sel_hi:[1,0,0] neg_lo:[0,0,1] neg_hi:[0,0,1]
	v_add_f32_e32 v8, v8, v8
	v_mov_b32_e32 v25, v19
	s_waitcnt lgkmcnt(0)
; DI float sin_t(float turns) { return __builtin_amdgcn_sinf(__builtin_amdgcn_fractf(turns)); }
; DI float cos_t(float turns) { return __builtin_amdgcn_cosf(__builtin_amdgcn_fractf(turns)); }
; DI float2 cmul(float2 a, float2 b) { return make_float2(a.x * b.x - a.y * b.y, a.x * b.y + a.y * b.x); }
; template <int N, bool INV>
; DI void fft_lds(float2* s) {
;     ...
; #pragma unroll 4
;       for (int it = 0; it < N / 4 / NT; ++it) {
;         int idx = tid + it * NT;
;         int j = idx & (q - 1), blk = idx >> lq;
;         int p0 = blk * 4 * q + j;
;         float f = (float)j * inv4q;
;         float2 t1 = make_float2(cos_t(f), -sin_t(f));
;         float2 t2 = cmul(t1, t1);
;         float2 x0 = s[phys(p0)], x1 = s[phys(p0 + q)], x2 = s[phys(p0 + 2 * q)], x3 = s[phys(p0 + 3 * q)];
;         float2 a0 = make_float2(x0.x + x2.x, x0.y + x2.y);
;         float2 a2 = cmul(make_float2(x0.x - x2.x, x0.y - x2.y), t1);
;         float2 a1 = make_float2(x1.x + x3.x, x1.y + x3.y);
;         float2 d3 = make_float2(x1.x - x3.x, x1.y - x3.y);
;         float2 a3 = cmul(make_float2(d3.y, -d3.x), t1);
;         s[phys(p0)] = make_float2(a0.x + a1.x, a0.y + a1.y);
;         s[phys(p0 + q)] = cmul(make_float2(a0.x - a1.x, a0.y - a1.y), t2);
;         s[phys(p0 + 2 * q)] = make_float2(a2.x + a3.x, a2.y + a3.y);
;         s[phys(p0 + 3 * q)] = cmul(make_float2(a2.x - a3.x, a2.y - a3.y), t2);
;       }
	v_pk_add_f32 v[18:19], v[12:13], v[16:17] neg_lo:[0,1] neg_hi:[0,1]
	v_pk_add_f32 v[12:13], v[12:13], v[16:17]
	v_xor_b32_e32 v23, 0x80000000, v18
	v_pk_add_f32 v[14:15], v[10:11], v[12:13]
	v_pk_add_f32 v[10:11], v[10:11], v[12:13] neg_lo:[0,1] neg_hi:[0,1]
	v_mov_b32_e32 v22, v19
	v_pk_mul_f32 v[18:19], v[20:21], v[18:19] op_sel_hi:[0,1]
	v_pk_mul_f32 v[12:13], v[8:9], v[10:11] op_sel_hi:[0,1]
	v_pk_add_f32 v[6:7], v[6:7], v[6:7] op_sel:[0,1] op_sel_hi:[0,1] neg_lo:[0,1] neg_hi:[0,1]
	v_pk_fma_f32 v[4:5], v[4:5], v[22:23], v[18:19] op_sel_hi:[0,1,1] neg_lo:[0,0,1] neg_hi:[0,0,1]
	ds_write_b64 v21, v[14:15]
	v_pk_fma_f32 v[14:15], v[6:7], v[10:11], v[12:13] op_sel:[0,0,1] op_sel_hi:[1,1,0] neg_lo:[0,0,1] neg_hi:[0,0,1]
	v_pk_fma_f32 v[10:11], v[6:7], v[10:11], v[12:13] op_sel:[0,0,1] op_sel_hi:[1,1,0]
	s_nop 0
	v_mov_b32_e32 v15, v11
	v_pk_add_f32 v[10:11], v[24:25], v[4:5]
	v_pk_add_f32 v[4:5], v[24:25], v[4:5] neg_lo:[0,1] neg_hi:[0,1]
	ds_write_b64 v26, v[14:15]
	v_pk_mul_f32 v[8:9], v[8:9], v[4:5] op_sel_hi:[0,1]
	ds_write_b64 v27, v[10:11]
	v_pk_fma_f32 v[10:11], v[6:7], v[4:5], v[8:9] op_sel:[0,0,1] op_sel_hi:[1,1,0] neg_lo:[0,0,1] neg_hi:[0,0,1]
	v_pk_fma_f32 v[4:5], v[6:7], v[4:5], v[8:9] op_sel:[0,0,1] op_sel_hi:[1,1,0]
	s_nop 0
	v_add_u32_e32 v4, 0x400, v3
	v_mov_b32_e32 v11, v5
	v_and_b32_e32 v9, s4, v4
	v_ashrrev_i32_e32 v4, s0, v4
	ds_write_b64 v28, v[10:11]
	v_lshlrev_b32_e32 v10, 2, v4
	v_lshl_add_u32 v11, v10, s0, v9
	v_ashrrev_i32_e32 v12, 4, v11
	v_add_lshl_u32 v21, v12, v11, 3
	v_add_u32_e32 v11, s1, v11
	v_cvt_f32_u32_e32 v4, v9
	v_ashrrev_i32_e32 v12, 4, v11
	v_add_lshl_u32 v26, v12, v11, 3
	v_or_b32_e32 v11, 2, v10
	v_or_b32_e32 v10, 3, v10
	v_lshl_add_u32 v11, v11, s0, v9
	v_lshl_add_u32 v9, v10, s0, v9
	v_mul_f32_e32 v4, v2, v4
	v_ashrrev_i32_e32 v12, 4, v11
	v_ashrrev_i32_e32 v10, 4, v9
	v_fract_f32_e32 v5, v4
	v_add_lshl_u32 v27, v12, v11, 3
	v_add_lshl_u32 v28, v10, v9, 3
	v_cos_f32_e32 v4, v5
	v_sin_f32_e32 v5, v5
	ds_read_b64 v[10:11], v21
	ds_read_b64 v[12:13], v26
	ds_read_b64 v[14:15], v27
	ds_read_b64 v[16:17], v28
	v_mov_b32_e32 v20, v5
	v_mul_f32_e64 v8, v4, -v5
	v_pk_mul_f32 v[6:7], v[4:5], v[4:5]
	s_waitcnt lgkmcnt(1)
	v_pk_add_f32 v[18:19], v[10:11], v[14:15] neg_lo:[0,1] neg_hi:[0,1]
	v_pk_add_f32 v[10:11], v[10:11], v[14:15]
	v_pk_mul_f32 v[22:23], v[20:21], v[18:19] op_sel_hi:[0,1]
	v_pk_fma_f32 v[24:25], v[18:19], v[4:5], v[22:23] op_sel:[0,0,1] op_sel_hi:[1,1,0]
	v_pk_fma_f32 v[18:19], v[18:19], v[4:5], v[22:23] op_sel:[0,0,1] op_sel_hi:[1,0,0] neg_lo:[0,0,1] neg_hi:[0,0,1]
	v_add_f32_e32 v8, v8, v8
	v_mov_b32_e32 v25, v19
	s_waitcnt lgkmcnt(0)
	v_pk_add_f32 v[18:19], v[12:13], v[16:17] neg_lo:[0,1] neg_hi:[0,1]
	v_pk_add_f32 v[12:13], v[12:13], v[16:17]
	v_xor_b32_e32 v23, 0x80000000, v18
	v_pk_add_f32 v[14:15], v[10:11], v[12:13]
	v_pk_add_f32 v[10:11], v[10:11], v[12:13] neg_lo:[0,1] neg_hi:[0,1]
	v_mov_b32_e32 v22, v19
	v_pk_mul_f32 v[18:19], v[20:21], v[18:19] op_sel_hi:[0,1]
	v_pk_mul_f32 v[12:13], v[8:9], v[10:11] op_sel_hi:[0,1]
	v_pk_add_f32 v[6:7], v[6:7], v[6:7] op_sel:[0,1] op_sel_hi:[0,1] neg_lo:[0,1] neg_hi:[0,1]
	v_pk_fma_f32 v[4:5], v[4:5], v[22:23], v[18:19] op_sel_hi:[0,1,1] neg_lo:[0,0,1] neg_hi:[0,0,1]
	ds_write_b64 v21, v[14:15]
	v_pk_fma_f32 v[14:15], v[6:7], v[10:11], v[12:13] op_sel:[0,0,1] op_sel_hi:[1,1,0] neg_lo:[0,0,1] neg_hi:[0,0,1]
	v_pk_fma_f32 v[10:11], v[6:7], v[10:11], v[12:13] op_sel:[0,0,1] op_sel_hi:[1,1,0]
	v_add_u32_e32 v3, 0x600, v3
	v_mov_b32_e32 v15, v11
	v_pk_add_f32 v[10:11], v[24:25], v[4:5]
	v_pk_add_f32 v[4:5], v[24:25], v[4:5] neg_lo:[0,1] neg_hi:[0,1]
	ds_write_b64 v26, v[14:15]
	v_pk_mul_f32 v[8:9], v[8:9], v[4:5] op_sel_hi:[0,1]
	ds_write_b64 v27, v[10:11]
	v_pk_fma_f32 v[10:11], v[6:7], v[4:5], v[8:9] op_sel:[0,0,1] op_sel_hi:[1,1,0] neg_lo:[0,0,1] neg_hi:[0,0,1]
	v_pk_fma_f32 v[4:5], v[6:7], v[4:5], v[8:9] op_sel:[0,0,1] op_sel_hi:[1,1,0]
	v_and_b32_e32 v9, s4, v3
	v_ashrrev_i32_e32 v3, s0, v3
	v_mov_b32_e32 v11, v5
	v_lshlrev_b32_e32 v3, 2, v3
	ds_write_b64 v28, v[10:11]
	v_lshl_add_u32 v10, v3, s0, v9
	v_ashrrev_i32_e32 v11, 4, v10
	v_add_lshl_u32 v21, v11, v10, 3
	v_add_u32_e32 v10, s1, v10
	v_cvt_f32_u32_e32 v4, v9
	v_ashrrev_i32_e32 v11, 4, v10
	v_add_lshl_u32 v26, v11, v10, 3
	v_or_b32_e32 v10, 2, v3
	v_or_b32_e32 v3, 3, v3
	v_lshl_add_u32 v10, v10, s0, v9
	v_lshl_add_u32 v3, v3, s0, v9
	v_mul_f32_e32 v4, v2, v4
	v_ashrrev_i32_e32 v11, 4, v10
	v_ashrrev_i32_e32 v9, 4, v3
	v_fract_f32_e32 v5, v4
	v_add_lshl_u32 v27, v11, v10, 3
	v_lshlrev_b32_e32 v9, 3, v9
	v_lshlrev_b32_e32 v3, 3, v3
	v_cos_f32_e32 v4, v5
	v_sin_f32_e32 v5, v5
	v_add3_u32 v3, 0, v9, v3
	ds_read_b64 v[10:11], v21
	ds_read_b64 v[12:13], v26
	ds_read_b64 v[14:15], v27
	ds_read_b64 v[16:17], v3
	v_mov_b32_e32 v20, v5
	v_mul_f32_e64 v8, v4, -v5
	v_pk_mul_f32 v[6:7], v[4:5], v[4:5]
	s_waitcnt lgkmcnt(1)
	v_pk_add_f32 v[18:19], v[10:11], v[14:15] neg_lo:[0,1] neg_hi:[0,1]
	v_pk_add_f32 v[10:11], v[10:11], v[14:15]
	v_pk_mul_f32 v[22:23], v[20:21], v[18:19] op_sel_hi:[0,1]
	v_pk_fma_f32 v[24:25], v[18:19], v[4:5], v[22:23] op_sel:[0,0,1] op_sel_hi:[1,1,0]
	v_pk_fma_f32 v[18:19], v[18:19], v[4:5], v[22:23] op_sel:[0,0,1] op_sel_hi:[1,0,0] neg_lo:[0,0,1] neg_hi:[0,0,1]
	v_add_f32_e32 v8, v8, v8
	v_mov_b32_e32 v25, v19
	s_waitcnt lgkmcnt(0)
	v_pk_add_f32 v[18:19], v[12:13], v[16:17] neg_lo:[0,1] neg_hi:[0,1]
	v_pk_add_f32 v[12:13], v[12:13], v[16:17]
	v_xor_b32_e32 v23, 0x80000000, v18
	v_pk_add_f32 v[14:15], v[10:11], v[12:13]
	v_pk_add_f32 v[10:11], v[10:11], v[12:13] neg_lo:[0,1] neg_hi:[0,1]
	v_mov_b32_e32 v22, v19
	v_pk_mul_f32 v[18:19], v[20:21], v[18:19] op_sel_hi:[0,1]
	v_pk_mul_f32 v[12:13], v[8:9], v[10:11] op_sel_hi:[0,1]
	v_pk_add_f32 v[6:7], v[6:7], v[6:7] op_sel:[0,1] op_sel_hi:[0,1] neg_lo:[0,1] neg_hi:[0,1]
	v_pk_fma_f32 v[4:5], v[4:5], v[22:23], v[18:19] op_sel_hi:[0,1,1] neg_lo:[0,0,1] neg_hi:[0,0,1]
	ds_write_b64 v21, v[14:15]
	v_pk_fma_f32 v[14:15], v[6:7], v[10:11], v[12:13] op_sel:[0,0,1] op_sel_hi:[1,1,0] neg_lo:[0,0,1] neg_hi:[0,0,1]
	v_pk_fma_f32 v[10:11], v[6:7], v[10:11], v[12:13] op_sel:[0,0,1] op_sel_hi:[1,1,0]
	s_nop 0
	v_mov_b32_e32 v15, v11
	v_pk_add_f32 v[10:11], v[24:25], v[4:5]
	v_pk_add_f32 v[4:5], v[24:25], v[4:5] neg_lo:[0,1] neg_hi:[0,1]
	ds_write_b64 v26, v[14:15]
	v_pk_mul_f32 v[8:9], v[8:9], v[4:5] op_sel_hi:[0,1]
	ds_write_b64 v27, v[10:11]
	v_pk_fma_f32 v[10:11], v[6:7], v[4:5], v[8:9] op_sel:[0,0,1] op_sel_hi:[1,1,0] neg_lo:[0,0,1] neg_hi:[0,0,1]
	v_pk_fma_f32 v[4:5], v[6:7], v[4:5], v[8:9] op_sel:[0,0,1] op_sel_hi:[1,1,0]
	s_nop 0
	v_mov_b32_e32 v11, v5
	ds_write_b64 v3, v[10:11]
	s_cbranch_scc0 .LBB0_473
	s_branch .Lfft_done_0
; DI float sin_t(float turns) { return __builtin_amdgcn_sinf(__builtin_amdgcn_fractf(turns)); }
; DI float cos_t(float turns) { return __builtin_amdgcn_cosf(__builtin_amdgcn_fractf(turns)); }
; DI float2 cmul(float2 a, float2 b) { return make_float2(a.x * b.x - a.y * b.y, a.x * b.y + a.y * b.x); }
; template <int N, bool INV>
; DI void fft_lds(float2* s) {
;     ...
; #pragma unroll 4
;       for (int it = 0; it < N / 4 / NT; ++it) {
;         int idx = tid + it * NT;
;         int j = idx & (q - 1), blk = idx >> lq;
;         int p0 = blk * 4 * q + j;
;         float f = (float)j * inv4q;
;         float2 t1 = make_float2(cos_t(f), -sin_t(f));
;         float2 t2 = cmul(t1, t1);
;         float2 x0 = s[phys(p0)], x1 = s[phys(p0 + q)], x2 = s[phys(p0 + 2 * q)], x3 = s[phys(p0 + 3 * q)];
;         float2 a0 = make_float2(x0.x + x2.x, x0.y + x2.y);
;         float2 a2 = cmul(make_float2(x0.x - x2.x, x0.y - x2.y), t1);
;         float2 a1 = make_float2(x1.x + x3.x, x1.y + x3.y);
;         float2 d3 = make_float2(x1.x - x3.x, x1.y - x3.y);
;         float2 a3 = cmul(make_float2(d3.y, -d3.x), t1);
;         s[phys(p0)] = make_float2(a0.x + a1.x, a0.y + a1.y);
;         s[phys(p0 + q)] = cmul(make_float2(a0.x - a1.x, a0.y - a1.y), t2);
;         s[phys(p0 + 2 * q)] = make_float2(a2.x + a3.x, a2.y + a3.y);
;         s[phys(p0 + 3 * q)] = cmul(make_float2(a2.x - a3.x, a2.y - a3.y), t2);
;       }
.Lfft_fast_0:
	v_add_u32_e32 v3, s5, v1
	v_ashrrev_i32_e32 v4, s0, v3
	v_and_b32_e32 v9, s4, v3
	v_lshlrev_b32_e32 v10, 2, v4
	v_lshl_add_u32 v11, v10, s0, v9
	v_ashrrev_i32_e32 v12, 4, v11
	v_add_lshl_u32 v21, v12, v11, 3
	v_cvt_f32_u32_e32 v4, v9
	v_mul_f32_e32 v4, v2, v4
	v_fract_f32_e32 v5, v4
	v_add_u32_e32 v26, s32, v21
	v_add_u32_e32 v27, s32, v26
	v_add_u32_e32 v28, s32, v27
	v_cos_f32_e32 v4, v5
	v_sin_f32_e32 v5, v5
	ds_read_b64 v[10:11], v21
	ds_read_b64 v[12:13], v26
	ds_read_b64 v[14:15], v27
	ds_read_b64 v[16:17], v28
	v_mov_b32_e32 v20, v5
	v_mul_f32_e64 v8, v4, -v5
	v_pk_mul_f32 v[6:7], v[4:5], v[4:5]
	s_waitcnt lgkmcnt(1)
	v_pk_add_f32 v[18:19], v[10:11], v[14:15] neg_lo:[0,1] neg_hi:[0,1]
	v_pk_add_f32 v[10:11], v[10:11], v[14:15]
	v_pk_mul_f32 v[22:23], v[20:21], v[18:19] op_sel_hi:[0,1]
	v_pk_fma_f32 v[24:25], v[18:19], v[4:5], v[22:23] op_sel:[0,0,1] op_sel_hi:[1,1,0]
	v_pk_fma_f32 v[18:19], v[18:19], v[4:5], v[22:23] op_sel:[0,0,1] op_sel_hi:[1,0,0] neg_lo:[0,0,1] neg_hi:[0,0,1]
	v_add_f32_e32 v8, v8, v8
	v_mov_b32_e32 v25, v19
	s_waitcnt lgkmcnt(0)
	v_pk_add_f32 v[18:19], v[12:13], v[16:17] neg_lo:[0,1] neg_hi:[0,1]
	v_pk_add_f32 v[12:13], v[12:13], v[16:17]
	v_xor_b32_e32 v23, 0x80000000, v18
	v_pk_add_f32 v[14:15], v[10:11], v[12:13]
	v_pk_add_f32 v[10:11], v[10:11], v[12:13] neg_lo:[0,1] neg_hi:[0,1]
	v_mov_b32_e32 v22, v19
	v_pk_mul_f32 v[18:19], v[20:21], v[18:19] op_sel_hi:[0,1]
	v_pk_mul_f32 v[12:13], v[8:9], v[10:11] op_sel_hi:[0,1]
	v_pk_add_f32 v[6:7], v[6:7], v[6:7] op_sel:[0,1] op_sel_hi:[0,1] neg_lo:[0,1] neg_hi:[0,1]
	v_pk_fma_f32 v[4:5], v[4:5], v[22:23], v[18:19] op_sel_hi:[0,1,1] neg_lo:[0,0,1] neg_hi:[0,0,1]
	ds_write_b64 v21, v[14:15]
	v_pk_fma_f32 v[14:15], v[6:7], v[10:11], v[12:13] op_sel:[0,0,1] op_sel_hi:[1,1,0] neg_lo:[0,0,1] neg_hi:[0,0,1]
	v_pk_fma_f32 v[10:11], v[6:7], v[10:11], v[12:13] op_sel:[0,0,1] op_sel_hi:[1,1,0]
	s_addk_i32 s5, 0x800
	v_mov_b32_e32 v15, v11
	v_pk_add_f32 v[10:11], v[24:25], v[4:5]
	v_pk_add_f32 v[4:5], v[24:25], v[4:5] neg_lo:[0,1] neg_hi:[0,1]
	ds_write_b64 v26, v[14:15]
	v_pk_mul_f32 v[8:9], v[8:9], v[4:5] op_sel_hi:[0,1]
	ds_write_b64 v27, v[10:11]
	v_pk_fma_f32 v[10:11], v[6:7], v[4:5], v[8:9] op_sel:[0,0,1] op_sel_hi:[1,1,0] neg_lo:[0,0,1] neg_hi:[0,0,1]
	v_pk_fma_f32 v[4:5], v[6:7], v[4:5], v[8:9] op_sel:[0,0,1] op_sel_hi:[1,1,0]
	s_cmpk_eq_i32 s5, 0x1000
	v_add_u32_e32 v4, 0x200, v3
	v_mov_b32_e32 v11, v5
	v_and_b32_e32 v9, s4, v4
	v_ashrrev_i32_e32 v4, s0, v4
	ds_write_b64 v28, v[10:11]
	v_lshlrev_b32_e32 v10, 2, v4
	v_lshl_add_u32 v11, v10, s0, v9
	v_ashrrev_i32_e32 v12, 4, v11
	v_add_lshl_u32 v21, v12, v11, 3
	v_cvt_f32_u32_e32 v4, v9
	v_mul_f32_e32 v4, v2, v4
	v_fract_f32_e32 v5, v4
	v_add_u32_e32 v26, s32, v21
	v_add_u32_e32 v27, s32, v26
	v_add_u32_e32 v28, s32, v27
	v_cos_f32_e32 v4, v5
	v_sin_f32_e32 v5, v5
	ds_read_b64 v[10:11], v21
	ds_read_b64 v[12:13], v26
	ds_read_b64 v[14:15], v27
	ds_read_b64 v[16:17], v28
	v_mov_b32_e32 v20, v5
	v_mul_f32_e64 v8, v4, -v5
	v_pk_mul_f32 v[6:7], v[4:5], v[4:5]
	s_waitcnt lgkmcnt(1)
	v_pk_add_f32 v[18:19], v[10:11], v[14:15] neg_lo:[0,1] neg_hi:[0,1]
	v_pk_add_f32 v[10:11], v[10:11], v[14:15]
	v_pk_mul_f32 v[22:23], v[20:21], v[18:19] op_sel_hi:[0,1]
	v_pk_fma_f32 v[24:25], v[18:19], v[4:5], v[22:23] op_sel:[0,0,1] op_sel_hi:[1,1,0]
	v_pk_fma_f32 v[18:19], v[18:19], v[4:5], v[22:23] op_sel:[0,0,1] op_sel_hi:[1,0,0] neg_lo:[0,0,1] neg_hi:[0,0,1]
	v_add_f32_e32 v8, v8, v8
	v_mov_b32_e32 v25, v19
	s_waitcnt lgkmcnt(0)
	v_pk_add_f32 v[18:19], v[12:13], v[16:17] neg_lo:[0,1] neg_hi:[0,1]
	v_pk_add_f32 v[12:13], v[12:13], v[16:17]
	v_xor_b32_e32 v23, 0x80000000, v18
	v_pk_add_f32 v[14:15], v[10:11], v[12:13]
	v_pk_add_f32 v[10:11], v[10:11], v[12:13] neg_lo:[0,1] neg_hi:[0,1]
	v_mov_b32_e32 v22, v19
	v_pk_mul_f32 v[18:19], v[20:21], v[18:19] op_sel_hi:[0,1]
	v_pk_mul_f32 v[12:13], v[8:9], v[10:11] op_sel_hi:[0,1]
	v_pk_add_f32 v[6:7], v[6:7], v[6:7] op_sel:[0,1] op_sel_hi:[0,1] neg_lo:[0,1] neg_hi:[0,1]
	v_pk_fma_f32 v[4:5], v[4:5], v[22:23], v[18:19] op_sel_hi:[0,1,1] neg_lo:[0,0,1] neg_hi:[0,0,1]
	ds_write_b64 v21, v[14:15]
	v_pk_fma_f32 v[14:15], v[6:7], v[10:11], v[12:13] op_sel:[0,0,1] op_sel_hi:[1,1,0] neg_lo:[0,0,1] neg_hi:[0,0,1]
	v_pk_fma_f32 v[10:11], v[6:7], v[10:11], v[12:13] op_sel:[0,0,1] op_sel_hi:[1,1,0]
	s_nop 0
	v_mov_b32_e32 v15, v11
	v_pk_add_f32 v[10:11], v[24:25], v[4:5]
	v_pk_add_f32 v[4:5], v[24:25], v[4:5] neg_lo:[0,1] neg_hi:[0,1]
	ds_write_b64 v26, v[14:15]
	v_pk_mul_f32 v[8:9], v[8:9], v[4:5] op_sel_hi:[0,1]
	ds_write_b64 v27, v[10:11]
	v_pk_fma_f32 v[10:11], v[6:7], v[4:5], v[8:9] op_sel:[0,0,1] op_sel_hi:[1,1,0] neg_lo:[0,0,1] neg_hi:[0,0,1]
	v_pk_fma_f32 v[4:5], v[6:7], v[4:5], v[8:9] op_sel:[0,0,1] op_sel_hi:[1,1,0]
	s_nop 0
	v_add_u32_e32 v4, 0x400, v3
	v_mov_b32_e32 v11, v5
	v_and_b32_e32 v9, s4, v4
	v_ashrrev_i32_e32 v4, s0, v4
	ds_write_b64 v28, v[10:11]
	v_lshlrev_b32_e32 v10, 2, v4
	v_lshl_add_u32 v11, v10, s0, v9
	v_ashrrev_i32_e32 v12, 4, v11
	v_add_lshl_u32 v21, v12, v11, 3
	v_cvt_f32_u32_e32 v4, v9
	v_mul_f32_e32 v4, v2, v4
	v_fract_f32_e32 v5, v4
	v_add_u32_e32 v26, s32, v21
	v_add_u32_e32 v27, s32, v26
	v_add_u32_e32 v28, s32, v27
	v_cos_f32_e32 v4, v5
	v_sin_f32_e32 v5, v5
	ds_read_b64 v[10:11], v21
	ds_read_b64 v[12:13], v26
	ds_read_b64 v[14:15], v27
	ds_read_b64 v[16:17], v28
	v_mov_b32_e32 v20, v5
	v_mul_f32_e64 v8, v4, -v5
	v_pk_mul_f32 v[6:7], v[4:5], v[4:5]
	s_waitcnt lgkmcnt(1)
; DI float sin_t(float turns) { return __builtin_amdgcn_sinf(__builtin_amdgcn_fractf(turns)); }
; DI float cos_t(float turns) { return __builtin_amdgcn_cosf(__builtin_amdgcn_fractf(turns)); }
; DI float2 cmul(float2 a, float2 b) { return make_float2(a.x * b.x - a.y * b.y, a.x * b.y + a.y * b.x); }
; template <int N, bool INV>
; DI void fft_lds(float2* s) {
;     ...
;     for (int lq = (LG & 1) ? LG - 3 : LG - 2; lq >= 0; lq -= 2) {
;       const int q = 1 << lq;
;       __syncthreads();
;       const float inv4q = 1.0f / (float)(4 * q);
; #pragma unroll 4
;       for (int it = 0; it < N / 4 / NT; ++it) {
;         int idx = tid + it * NT;
;         int j = idx & (q - 1), blk = idx >> lq;
;         int p0 = blk * 4 * q + j;
;         float f = (float)j * inv4q;
;         float2 t1 = make_float2(cos_t(f), -sin_t(f));
;         float2 t2 = cmul(t1, t1);
;         float2 x0 = s[phys(p0)], x1 = s[phys(p0 + q)], x2 = s[phys(p0 + 2 * q)], x3 = s[phys(p0 + 3 * q)];
;         float2 a0 = make_float2(x0.x + x2.x, x0.y + x2.y);
;         float2 a2 = cmul(make_float2(x0.x - x2.x, x0.y - x2.y), t1);
;         float2 a1 = make_float2(x1.x + x3.x, x1.y + x3.y);
;         float2 d3 = make_float2(x1.x - x3.x, x1.y - x3.y);
;         float2 a3 = cmul(make_float2(d3.y, -d3.x), t1);
;         s[phys(p0)] = make_float2(a0.x + a1.x, a0.y + a1.y);
;         s[phys(p0 + q)] = cmul(make_float2(a0.x - a1.x, a0.y - a1.y), t2);
;         s[phys(p0 + 2 * q)] = make_float2(a2.x + a3.x, a2.y + a3.y);
;         s[phys(p0 + 3 * q)] = cmul(make_float2(a2.x - a3.x, a2.y - a3.y), t2);
;       }
; DI void hyena_lat_item(const P& p, int l, int c, int bp, unsigned char* lds) {
;     ...
;     fft_lds<16384, false>(s);
;     const float2* H = (const float2*)(p.ws + O_SPEC) + ((size_t)(l * 2 + ord) * 256 + c) * 16384;
; #pragma unroll 8
;     for (int i = tid; i < 16384; i += NT) { s[phys(i)] = cmul(s[phys(i)], H[i]); }
	v_pk_add_f32 v[18:19], v[10:11], v[14:15] neg_lo:[0,1] neg_hi:[0,1]
	v_pk_add_f32 v[10:11], v[10:11], v[14:15]
	v_pk_mul_f32 v[22:23], v[20:21], v[18:19] op_sel_hi:[0,1]
	v_pk_fma_f32 v[24:25], v[18:19], v[4:5], v[22:23] op_sel:[0,0,1] op_sel_hi:[1,1,0]
	v_pk_fma_f32 v[18:19], v[18:19], v[4:5], v[22:23] op_sel:[0,0,1] op_sel_hi:[1,0,0] neg_lo:[0,0,1] neg_hi:[0,0,1]
	v_add_f32_e32 v8, v8, v8
	v_mov_b32_e32 v25, v19
	s_waitcnt lgkmcnt(0)
	v_pk_add_f32 v[18:19], v[12:13], v[16:17] neg_lo:[0,1] neg_hi:[0,1]
	v_pk_add_f32 v[12:13], v[12:13], v[16:17]
	v_xor_b32_e32 v23, 0x80000000, v18
	v_pk_add_f32 v[14:15], v[10:11], v[12:13]
	v_pk_add_f32 v[10:11], v[10:11], v[12:13] neg_lo:[0,1] neg_hi:[0,1]
	v_mov_b32_e32 v22, v19
	v_pk_mul_f32 v[18:19], v[20:21], v[18:19] op_sel_hi:[0,1]
	v_pk_mul_f32 v[12:13], v[8:9], v[10:11] op_sel_hi:[0,1]
	v_pk_add_f32 v[6:7], v[6:7], v[6:7] op_sel:[0,1] op_sel_hi:[0,1] neg_lo:[0,1] neg_hi:[0,1]
	v_pk_fma_f32 v[4:5], v[4:5], v[22:23], v[18:19] op_sel_hi:[0,1,1] neg_lo:[0,0,1] neg_hi:[0,0,1]
	ds_write_b64 v21, v[14:15]
	v_pk_fma_f32 v[14:15], v[6:7], v[10:11], v[12:13] op_sel:[0,0,1] op_sel_hi:[1,1,0] neg_lo:[0,0,1] neg_hi:[0,0,1]
	v_pk_fma_f32 v[10:11], v[6:7], v[10:11], v[12:13] op_sel:[0,0,1] op_sel_hi:[1,1,0]
	v_add_u32_e32 v3, 0x600, v3
	v_mov_b32_e32 v15, v11
	v_pk_add_f32 v[10:11], v[24:25], v[4:5]
	v_pk_add_f32 v[4:5], v[24:25], v[4:5] neg_lo:[0,1] neg_hi:[0,1]
	ds_write_b64 v26, v[14:15]
	v_pk_mul_f32 v[8:9], v[8:9], v[4:5] op_sel_hi:[0,1]
	ds_write_b64 v27, v[10:11]
	v_pk_fma_f32 v[10:11], v[6:7], v[4:5], v[8:9] op_sel:[0,0,1] op_sel_hi:[1,1,0] neg_lo:[0,0,1] neg_hi:[0,0,1]
	v_pk_fma_f32 v[4:5], v[6:7], v[4:5], v[8:9] op_sel:[0,0,1] op_sel_hi:[1,1,0]
	v_and_b32_e32 v9, s4, v3
	v_ashrrev_i32_e32 v3, s0, v3
	v_mov_b32_e32 v11, v5
	v_lshlrev_b32_e32 v3, 2, v3
	ds_write_b64 v28, v[10:11]
	v_lshl_add_u32 v10, v3, s0, v9
	v_ashrrev_i32_e32 v11, 4, v10
	v_add_lshl_u32 v21, v11, v10, 3
	v_cvt_f32_u32_e32 v4, v9
	v_mul_f32_e32 v4, v2, v4
	v_fract_f32_e32 v5, v4
	v_cos_f32_e32 v4, v5
	v_sin_f32_e32 v5, v5
	v_add_u32_e32 v26, s32, v21
	v_add_u32_e32 v27, s32, v26
	v_add_u32_e32 v3, s32, v27
	ds_read_b64 v[10:11], v21
	ds_read_b64 v[12:13], v26
	ds_read_b64 v[14:15], v27
	ds_read_b64 v[16:17], v3
	v_mov_b32_e32 v20, v5
	v_mul_f32_e64 v8, v4, -v5
	v_pk_mul_f32 v[6:7], v[4:5], v[4:5]
	s_waitcnt lgkmcnt(1)
	v_pk_add_f32 v[18:19], v[10:11], v[14:15] neg_lo:[0,1] neg_hi:[0,1]
	v_pk_add_f32 v[10:11], v[10:11], v[14:15]
	v_pk_mul_f32 v[22:23], v[20:21], v[18:19] op_sel_hi:[0,1]
	v_pk_fma_f32 v[24:25], v[18:19], v[4:5], v[22:23] op_sel:[0,0,1] op_sel_hi:[1,1,0]
	v_pk_fma_f32 v[18:19], v[18:19], v[4:5], v[22:23] op_sel:[0,0,1] op_sel_hi:[1,0,0] neg_lo:[0,0,1] neg_hi:[0,0,1]
	v_add_f32_e32 v8, v8, v8
	v_mov_b32_e32 v25, v19
	s_waitcnt lgkmcnt(0)
	v_pk_add_f32 v[18:19], v[12:13], v[16:17] neg_lo:[0,1] neg_hi:[0,1]
	v_pk_add_f32 v[12:13], v[12:13], v[16:17]
	v_xor_b32_e32 v23, 0x80000000, v18
	v_pk_add_f32 v[14:15], v[10:11], v[12:13]
	v_pk_add_f32 v[10:11], v[10:11], v[12:13] neg_lo:[0,1] neg_hi:[0,1]
	v_mov_b32_e32 v22, v19
	v_pk_mul_f32 v[18:19], v[20:21], v[18:19] op_sel_hi:[0,1]
	v_pk_mul_f32 v[12:13], v[8:9], v[10:11] op_sel_hi:[0,1]
	v_pk_add_f32 v[6:7], v[6:7], v[6:7] op_sel:[0,1] op_sel_hi:[0,1] neg_lo:[0,1] neg_hi:[0,1]
	v_pk_fma_f32 v[4:5], v[4:5], v[22:23], v[18:19] op_sel_hi:[0,1,1] neg_lo:[0,0,1] neg_hi:[0,0,1]
	ds_write_b64 v21, v[14:15]
	v_pk_fma_f32 v[14:15], v[6:7], v[10:11], v[12:13] op_sel:[0,0,1] op_sel_hi:[1,1,0] neg_lo:[0,0,1] neg_hi:[0,0,1]
	v_pk_fma_f32 v[10:11], v[6:7], v[10:11], v[12:13] op_sel:[0,0,1] op_sel_hi:[1,1,0]
	s_nop 0
	v_mov_b32_e32 v15, v11
	v_pk_add_f32 v[10:11], v[24:25], v[4:5]
	v_pk_add_f32 v[4:5], v[24:25], v[4:5] neg_lo:[0,1] neg_hi:[0,1]
	ds_write_b64 v26, v[14:15]
	v_pk_mul_f32 v[8:9], v[8:9], v[4:5] op_sel_hi:[0,1]
	ds_write_b64 v27, v[10:11]
	v_pk_fma_f32 v[10:11], v[6:7], v[4:5], v[8:9] op_sel:[0,0,1] op_sel_hi:[1,1,0] neg_lo:[0,0,1] neg_hi:[0,0,1]
	v_pk_fma_f32 v[4:5], v[6:7], v[4:5], v[8:9] op_sel:[0,0,1] op_sel_hi:[1,1,0]
	s_nop 0
	v_mov_b32_e32 v11, v5
	ds_write_b64 v3, v[10:11]
	s_cbranch_scc0 .Lfft_fast_0
.Lfft_done_0:
	s_add_i32 s1, s0, -2
	s_cmp_eq_u32 s0, 0
	s_mov_b32 s0, s1
	s_cbranch_scc0 .LBB0_472
	s_movk_i32 s0, 0x4000
	v_max_i32_e32 v1, 0x3e00, v52
	v_cmp_gt_i32_e64 s[4:5], s0, v52
	v_sub_u32_e32 v70, v1, v52
	s_waitcnt lgkmcnt(0)
	s_barrier
	s_and_saveexec_b64 s[0:1], s[4:5]
	s_cbranch_execz .LBB0_483
	v_add_u32_e32 v1, 0x1ff, v70
	v_and_b32_e32 v2, 0xe00, v1
	s_movk_i32 s10, 0xe00
	v_cmp_ne_u32_e32 vcc, s10, v2
	v_mov_b32_e32 v2, v52
	s_and_saveexec_b64 s[10:11], vcc
	s_cbranch_execz .LBB0_480
	v_lshrrev_b32_e32 v2, 9, v1
	s_lshl_b64 s[12:13], s[6:7], 17
	v_readlane_b32 s16, v254, 60
	v_add_u32_e32 v2, 1, v2
	s_add_u32 s12, s16, s12
	v_readlane_b32 s16, v254, 61
	v_and_b32_e32 v2, 7, v2
	v_ashrrev_i32_e32 v53, 31, v52
	s_addc_u32 s13, s16, s13
	v_lshl_add_u64 v[4:5], v[52:53], 3, s[12:13]
	v_add_u32_e32 v3, 0, v50
	v_sub_u32_e32 v6, 0, v2
	s_mov_b64 s[12:13], 0
	v_mov_b32_e32 v2, v52
	s_mov_b64 s[16:17], 0x1000

; DI float sin_t(float turns) { return __builtin_amdgcn_sinf(__builtin_amdgcn_fractf(turns)); }
; DI float cos_t(float turns) { return __builtin_amdgcn_cosf(__builtin_amdgcn_fractf(turns)); }
; DI float2 cmul(float2 a, float2 b) { return make_float2(a.x * b.x - a.y * b.y, a.x * b.y + a.y * b.x); }
; template <int N, bool INV>
; DI void fft_lds(float2* s) {
;     ...
;     for (int lq = (LG & 1) ? LG - 3 : LG - 2; lq >= 0; lq -= 2) {
;       const int q = 1 << lq;
;       __syncthreads();
;       const float inv4q = 1.0f / (float)(4 * q);
; #pragma unroll 4
;       for (int it = 0; it < N / 4 / NT; ++it) {
;         int idx = tid + it * NT;
;         int j = idx & (q - 1), blk = idx >> lq;
;         int p0 = blk * 4 * q + j;
;         float f = (float)j * inv4q;
;         float2 t1 = make_float2(cos_t(f), -sin_t(f));
;         float2 t2 = cmul(t1, t1);
;         float2 x0 = s[phys(p0)], x1 = s[phys(p0 + q)], x2 = s[phys(p0 + 2 * q)], x3 = s[phys(p0 + 3 * q)];
;         float2 a0 = make_float2(x0.x + x2.x, x0.y + x2.y);
;         float2 a2 = cmul(make_float2(x0.x - x2.x, x0.y - x2.y), t1);
;         float2 a1 = make_float2(x1.x + x3.x, x1.y + x3.y);
;         float2 d3 = make_float2(x1.x - x3.x, x1.y - x3.y);
;         float2 a3 = cmul(make_float2(d3.y, -d3.x), t1);
;         s[phys(p0)] = make_float2(a0.x + a1.x, a0.y + a1.y);
;         s[phys(p0 + q)] = cmul(make_float2(a0.x - a1.x, a0.y - a1.y), t2);
;         s[phys(p0 + 2 * q)] = make_float2(a2.x + a3.x, a2.y + a3.y);
;         s[phys(p0 + 3 * q)] = cmul(make_float2(a2.x - a3.x, a2.y - a3.y), t2);
;       }
.LBB0_488:
	s_lshl_b32 s1, 4, s0
	v_cvt_f32_u32_e32 v3, s1
	s_lshl_b32 s1, 1, s0
	s_waitcnt lgkmcnt(0)
	s_barrier
	v_div_scale_f32 v4, s[10:11], v3, v3, 1.0
	v_rcp_f32_e32 v5, v4
	s_bfm_b32 s10, s0, 0
	s_mov_b32 s11, 0
	v_fma_f32 v6, -v4, v5, 1.0
	v_fmac_f32_e32 v5, v6, v5
	v_div_scale_f32 v6, vcc, 1.0, v3, 1.0
	v_mul_f32_e32 v7, v6, v5
	v_fma_f32 v8, -v4, v7, v6
	v_fmac_f32_e32 v7, v8, v5
	v_fma_f32 v4, -v4, v7, v6
	v_div_fmas_f32 v4, v4, v5, v7
	v_div_fixup_f32 v3, v4, v3, 1.0
	s_sub_i32 s32, s0, 4
	s_lshl_b32 s32, 0x88, s32
	s_cmp_lt_u32 s0, 4
	s_cbranch_scc0 .Lfft_fast_1
.LBB0_489:
	v_add_u32_e32 v21, s11, v2
	v_ashrrev_i32_e32 v4, s0, v21
	v_and_b32_e32 v9, s10, v21
	v_lshlrev_b32_e32 v10, 2, v4
	v_lshl_add_u32 v11, v10, s0, v9
	v_ashrrev_i32_e32 v12, 4, v11
	v_add_lshl_u32 v26, v12, v11, 3
	v_add_u32_e32 v11, s1, v11
	v_cvt_f32_u32_e32 v4, v9
	v_ashrrev_i32_e32 v12, 4, v11
	v_add_lshl_u32 v27, v12, v11, 3
	v_or_b32_e32 v11, 2, v10
	v_or_b32_e32 v10, 3, v10
	v_lshl_add_u32 v11, v11, s0, v9
	v_lshl_add_u32 v9, v10, s0, v9
	v_mul_f32_e32 v4, v3, v4
	v_ashrrev_i32_e32 v12, 4, v11
	v_ashrrev_i32_e32 v10, 4, v9
	v_fract_f32_e32 v5, v4
	v_add_lshl_u32 v28, v12, v11, 3
	v_add_lshl_u32 v29, v10, v9, 3
	v_cos_f32_e32 v4, v5
	v_sin_f32_e32 v5, v5
	ds_read_b64 v[10:11], v26
	ds_read_b64 v[12:13], v27
	ds_read_b64 v[14:15], v28
	ds_read_b64 v[16:17], v29
	v_mov_b32_e32 v20, v5
	v_mul_f32_e64 v8, v4, -v5
	v_pk_mul_f32 v[6:7], v[4:5], v[4:5]
	s_waitcnt lgkmcnt(1)
	v_pk_add_f32 v[18:19], v[10:11], v[14:15] neg_lo:[0,1] neg_hi:[0,1]
	v_pk_add_f32 v[10:11], v[10:11], v[14:15]
	v_pk_mul_f32 v[22:23], v[20:21], v[18:19] op_sel_hi:[0,1]
	v_pk_fma_f32 v[24:25], v[18:19], v[4:5], v[22:23] op_sel:[0,0,1] op_sel_hi:[1,1,0]
	v_pk_fma_f32 v[18:19], v[18:19], v[4:5], v[22:23] op_sel:[0,0,1] op_sel_hi:[1,0,0] neg_lo:[0,0,1] neg_hi:[0,0,1]
	v_add_f32_e32 v8, v8, v8
	v_mov_b32_e32 v25, v19
	s_waitcnt lgkmcnt(0)
	v_pk_add_f32 v[18:19], v[12:13], v[16:17] neg_lo:[0,1] neg_hi:[0,1]
	v_pk_add_f32 v[12:13], v[12:13], v[16:17]
	v_xor_b32_e32 v23, 0x80000000, v18
	v_pk_add_f32 v[14:15], v[10:11], v[12:13]
	v_pk_add_f32 v[10:11], v[10:11], v[12:13] neg_lo:[0,1] neg_hi:[0,1]
	v_mov_b32_e32 v22, v19
	v_pk_mul_f32 v[18:19], v[20:21], v[18:19] op_sel_hi:[0,1]
	v_pk_mul_f32 v[12:13], v[8:9], v[10:11] op_sel_hi:[0,1]
	v_pk_add_f32 v[6:7], v[6:7], v[6:7] op_sel:[0,1] op_sel_hi:[0,1] neg_lo:[0,1] neg_hi:[0,1]
	v_pk_fma_f32 v[4:5], v[4:5], v[22:23], v[18:19] op_sel_hi:[0,1,1] neg_lo:[0,0,1] neg_hi:[0,0,1]
	ds_write_b64 v26, v[14:15]
	v_pk_fma_f32 v[14:15], v[6:7], v[10:11], v[12:13] op_sel:[0,0,1] op_sel_hi:[1,1,0] neg_lo:[0,0,1] neg_hi:[0,0,1]
	v_pk_fma_f32 v[10:11], v[6:7], v[10:11], v[12:13] op_sel:[0,0,1] op_sel_hi:[1,1,0]
	s_addk_i32 s11, 0x800
	v_mov_b32_e32 v15, v11
	v_pk_add_f32 v[10:11], v[24:25], v[4:5]
	v_pk_add_f32 v[4:5], v[24:25], v[4:5] neg_lo:[0,1] neg_hi:[0,1]
	ds_write_b64 v27, v[14:15]
	v_pk_mul_f32 v[8:9], v[8:9], v[4:5] op_sel_hi:[0,1]
	ds_write_b64 v28, v[10:11]
	v_pk_fma_f32 v[10:11], v[6:7], v[4:5], v[8:9] op_sel:[0,0,1] op_sel_hi:[1,1,0] neg_lo:[0,0,1] neg_hi:[0,0,1]
	v_pk_fma_f32 v[4:5], v[6:7], v[4:5], v[8:9] op_sel:[0,0,1] op_sel_hi:[1,1,0]
	s_cmpk_lg_i32 s11, 0x1000
	v_add_u32_e32 v4, 0x200, v21
	v_mov_b32_e32 v11, v5
	v_and_b32_e32 v9, s10, v4
	v_ashrrev_i32_e32 v4, s0, v4
	ds_write_b64 v29, v[10:11]
	v_lshlrev_b32_e32 v10, 2, v4
	v_lshl_add_u32 v11, v10, s0, v9
	v_ashrrev_i32_e32 v12, 4, v11
	v_add_lshl_u32 v26, v12, v11, 3
	v_add_u32_e32 v11, s1, v11
	v_cvt_f32_u32_e32 v4, v9
	v_ashrrev_i32_e32 v12, 4, v11
	v_add_lshl_u32 v27, v12, v11, 3
	v_or_b32_e32 v11, 2, v10
	v_or_b32_e32 v10, 3, v10
	v_lshl_add_u32 v11, v11, s0, v9
	v_lshl_add_u32 v9, v10, s0, v9
	v_mul_f32_e32 v4, v3, v4
	v_ashrrev_i32_e32 v12, 4, v11
	v_ashrrev_i32_e32 v10, 4, v9
	v_fract_f32_e32 v5, v4
	v_add_lshl_u32 v28, v12, v11, 3
	v_add_lshl_u32 v29, v10, v9, 3
	v_cos_f32_e32 v4, v5
	v_sin_f32_e32 v5, v5
	ds_read_b64 v[10:11], v26
	ds_read_b64 v[12:13], v27
	ds_read_b64 v[14:15], v28
	ds_read_b64 v[16:17], v29
	v_mov_b32_e32 v20, v5
	v_mul_f32_e64 v8, v4, -v5
	v_pk_mul_f32 v[6:7], v[4:5], v[4:5]
	s_waitcnt lgkmcnt(1)
	v_pk_add_f32 v[18:19], v[10:11], v[14:15] neg_lo:[0,1] neg_hi:[0,1]
	v_pk_add_f32 v[10:11], v[10:11], v[14:15]
	v_pk_mul_f32 v[22:23], v[20:21], v[18:19] op_sel_hi:[0,1]
	v_pk_fma_f32 v[24:25], v[18:19], v[4:5], v[22:23] op_sel:[0,0,1] op_sel_hi:[1,1,0]
	v_pk_fma_f32 v[18:19], v[18:19], v[4:5], v[22:23] op_sel:[0,0,1] op_sel_hi:[1,0,0] neg_lo:[0,0,1] neg_hi:[0,0,1]
	v_add_f32_e32 v8, v8, v8
	v_mov_b32_e32 v25, v19
	s_waitcnt lgkmcnt(0)
; DI float sin_t(float turns) { return __builtin_amdgcn_sinf(__builtin_amdgcn_fractf(turns)); }
; DI float cos_t(float turns) { return __builtin_amdgcn_cosf(__builtin_amdgcn_fractf(turns)); }
; DI float2 cmul(float2 a, float2 b) { return make_float2(a.x * b.x - a.y * b.y, a.x * b.y + a.y * b.x); }
; template <int N, bool INV>
; DI void fft_lds(float2* s) {
;     ...
; #pragma unroll 4
;       for (int it = 0; it < N / 4 / NT; ++it) {
;         int idx = tid + it * NT;
;         int j = idx & (q - 1), blk = idx >> lq;
;         int p0 = blk * 4 * q + j;
;         float f = (float)j * inv4q;
;         float2 t1 = make_float2(cos_t(f), -sin_t(f));
;         float2 t2 = cmul(t1, t1);
;         float2 x0 = s[phys(p0)], x1 = s[phys(p0 + q)], x2 = s[phys(p0 + 2 * q)], x3 = s[phys(p0 + 3 * q)];
;         float2 a0 = make_float2(x0.x + x2.x, x0.y + x2.y);
;         float2 a2 = cmul(make_float2(x0.x - x2.x, x0.y - x2.y), t1);
;         float2 a1 = make_float2(x1.x + x3.x, x1.y + x3.y);
;         float2 d3 = make_float2(x1.x - x3.x, x1.y - x3.y);
;         float2 a3 = cmul(make_float2(d3.y, -d3.x), t1);
;         s[phys(p0)] = make_float2(a0.x + a1.x, a0.y + a1.y);
;         s[phys(p0 + q)] = cmul(make_float2(a0.x - a1.x, a0.y - a1.y), t2);
;         s[phys(p0 + 2 * q)] = make_float2(a2.x + a3.x, a2.y + a3.y);
;         s[phys(p0 + 3 * q)] = cmul(make_float2(a2.x - a3.x, a2.y - a3.y), t2);
;       }
	v_pk_add_f32 v[18:19], v[12:13], v[16:17] neg_lo:[0,1] neg_hi:[0,1]
	v_pk_add_f32 v[12:13], v[12:13], v[16:17]
	v_xor_b32_e32 v23, 0x80000000, v18
	v_pk_add_f32 v[14:15], v[10:11], v[12:13]
	v_pk_add_f32 v[10:11], v[10:11], v[12:13] neg_lo:[0,1] neg_hi:[0,1]
	v_mov_b32_e32 v22, v19
	v_pk_mul_f32 v[18:19], v[20:21], v[18:19] op_sel_hi:[0,1]
	v_pk_mul_f32 v[12:13], v[8:9], v[10:11] op_sel_hi:[0,1]
	v_pk_add_f32 v[6:7], v[6:7], v[6:7] op_sel:[0,1] op_sel_hi:[0,1] neg_lo:[0,1] neg_hi:[0,1]
	v_pk_fma_f32 v[4:5], v[4:5], v[22:23], v[18:19] op_sel_hi:[0,1,1] neg_lo:[0,0,1] neg_hi:[0,0,1]
	ds_write_b64 v26, v[14:15]
	v_pk_fma_f32 v[14:15], v[6:7], v[10:11], v[12:13] op_sel:[0,0,1] op_sel_hi:[1,1,0] neg_lo:[0,0,1] neg_hi:[0,0,1]
	v_pk_fma_f32 v[10:11], v[6:7], v[10:11], v[12:13] op_sel:[0,0,1] op_sel_hi:[1,1,0]
	s_nop 0
	v_mov_b32_e32 v15, v11
	v_pk_add_f32 v[10:11], v[24:25], v[4:5]
	v_pk_add_f32 v[4:5], v[24:25], v[4:5] neg_lo:[0,1] neg_hi:[0,1]
	ds_write_b64 v27, v[14:15]
	v_pk_mul_f32 v[8:9], v[8:9], v[4:5] op_sel_hi:[0,1]
	ds_write_b64 v28, v[10:11]
	v_pk_fma_f32 v[10:11], v[6:7], v[4:5], v[8:9] op_sel:[0,0,1] op_sel_hi:[1,1,0] neg_lo:[0,0,1] neg_hi:[0,0,1]
	v_pk_fma_f32 v[4:5], v[6:7], v[4:5], v[8:9] op_sel:[0,0,1] op_sel_hi:[1,1,0]
	s_nop 0
	v_add_u32_e32 v4, 0x400, v21
	v_mov_b32_e32 v11, v5
	v_and_b32_e32 v9, s10, v4
	v_ashrrev_i32_e32 v4, s0, v4
	ds_write_b64 v29, v[10:11]
	v_lshlrev_b32_e32 v10, 2, v4
	v_lshl_add_u32 v11, v10, s0, v9
	v_ashrrev_i32_e32 v12, 4, v11
	v_add_lshl_u32 v26, v12, v11, 3
	v_add_u32_e32 v11, s1, v11
	v_cvt_f32_u32_e32 v4, v9
	v_ashrrev_i32_e32 v12, 4, v11
	v_add_lshl_u32 v27, v12, v11, 3
	v_or_b32_e32 v11, 2, v10
	v_or_b32_e32 v10, 3, v10
	v_lshl_add_u32 v11, v11, s0, v9
	v_lshl_add_u32 v9, v10, s0, v9
	v_mul_f32_e32 v4, v3, v4
	v_ashrrev_i32_e32 v12, 4, v11
	v_ashrrev_i32_e32 v10, 4, v9
	v_fract_f32_e32 v5, v4
	v_add_lshl_u32 v28, v12, v11, 3
	v_add_lshl_u32 v29, v10, v9, 3
	v_cos_f32_e32 v4, v5
	v_sin_f32_e32 v5, v5
	ds_read_b64 v[10:11], v26
	ds_read_b64 v[12:13], v27
	ds_read_b64 v[14:15], v28
	ds_read_b64 v[16:17], v29
	v_mov_b32_e32 v20, v5
	v_mul_f32_e64 v8, v4, -v5
	v_pk_mul_f32 v[6:7], v[4:5], v[4:5]
	s_waitcnt lgkmcnt(1)
	v_pk_add_f32 v[18:19], v[10:11], v[14:15] neg_lo:[0,1] neg_hi:[0,1]
	v_pk_add_f32 v[10:11], v[10:11], v[14:15]
	v_pk_mul_f32 v[22:23], v[20:21], v[18:19] op_sel_hi:[0,1]
	v_pk_fma_f32 v[24:25], v[18:19], v[4:5], v[22:23] op_sel:[0,0,1] op_sel_hi:[1,1,0]
	v_pk_fma_f32 v[18:19], v[18:19], v[4:5], v[22:23] op_sel:[0,0,1] op_sel_hi:[1,0,0] neg_lo:[0,0,1] neg_hi:[0,0,1]
	v_add_f32_e32 v8, v8, v8
	v_mov_b32_e32 v25, v19
	s_waitcnt lgkmcnt(0)
	v_pk_add_f32 v[18:19], v[12:13], v[16:17] neg_lo:[0,1] neg_hi:[0,1]
	v_pk_add_f32 v[12:13], v[12:13], v[16:17]
	v_xor_b32_e32 v23, 0x80000000, v18
	v_pk_add_f32 v[14:15], v[10:11], v[12:13]
	v_pk_add_f32 v[10:11], v[10:11], v[12:13] neg_lo:[0,1] neg_hi:[0,1]
	v_mov_b32_e32 v22, v19
	v_pk_mul_f32 v[18:19], v[20:21], v[18:19] op_sel_hi:[0,1]
	v_pk_mul_f32 v[12:13], v[8:9], v[10:11] op_sel_hi:[0,1]
	v_pk_add_f32 v[6:7], v[6:7], v[6:7] op_sel:[0,1] op_sel_hi:[0,1] neg_lo:[0,1] neg_hi:[0,1]
	v_pk_fma_f32 v[4:5], v[4:5], v[22:23], v[18:19] op_sel_hi:[0,1,1] neg_lo:[0,0,1] neg_hi:[0,0,1]
	ds_write_b64 v26, v[14:15]
	v_pk_fma_f32 v[14:15], v[6:7], v[10:11], v[12:13] op_sel:[0,0,1] op_sel_hi:[1,1,0] neg_lo:[0,0,1] neg_hi:[0,0,1]
	v_pk_fma_f32 v[10:11], v[6:7], v[10:11], v[12:13] op_sel:[0,0,1] op_sel_hi:[1,1,0]
	s_nop 0
	v_mov_b32_e32 v15, v11
	v_pk_add_f32 v[10:11], v[24:25], v[4:5]
	v_pk_add_f32 v[4:5], v[24:25], v[4:5] neg_lo:[0,1] neg_hi:[0,1]
	ds_write_b64 v27, v[14:15]
	v_pk_mul_f32 v[8:9], v[8:9], v[4:5] op_sel_hi:[0,1]
	ds_write_b64 v28, v[10:11]
	v_pk_fma_f32 v[10:11], v[6:7], v[4:5], v[8:9] op_sel:[0,0,1] op_sel_hi:[1,1,0] neg_lo:[0,0,1] neg_hi:[0,0,1]
	v_pk_fma_f32 v[4:5], v[6:7], v[4:5], v[8:9] op_sel:[0,0,1] op_sel_hi:[1,1,0]
	s_nop 0
	v_add_u32_e32 v4, 0x600, v21
	v_mov_b32_e32 v11, v5
	v_and_b32_e32 v9, s10, v4
	v_ashrrev_i32_e32 v4, s0, v4
	ds_write_b64 v29, v[10:11]
	v_lshlrev_b32_e32 v10, 2, v4
	v_lshl_add_u32 v11, v10, s0, v9
	v_ashrrev_i32_e32 v12, 4, v11
	v_add_lshl_u32 v21, v12, v11, 3
	v_add_u32_e32 v11, s1, v11
	v_cvt_f32_u32_e32 v4, v9
	v_ashrrev_i32_e32 v12, 4, v11
	v_add_lshl_u32 v26, v12, v11, 3
	v_or_b32_e32 v11, 2, v10
	v_or_b32_e32 v10, 3, v10
	v_lshl_add_u32 v11, v11, s0, v9
	v_lshl_add_u32 v9, v10, s0, v9
	v_mul_f32_e32 v4, v3, v4
	v_ashrrev_i32_e32 v12, 4, v11
	v_ashrrev_i32_e32 v10, 4, v9
	v_fract_f32_e32 v5, v4
	v_add_lshl_u32 v27, v12, v11, 3
	v_add_lshl_u32 v28, v10, v9, 3
	v_cos_f32_e32 v4, v5
	v_sin_f32_e32 v5, v5
	ds_read_b64 v[10:11], v21
	ds_read_b64 v[12:13], v26
	ds_read_b64 v[14:15], v27
	ds_read_b64 v[16:17], v28
	v_mov_b32_e32 v20, v5
	v_mul_f32_e64 v8, v4, -v5
	v_pk_mul_f32 v[6:7], v[4:5], v[4:5]
	s_waitcnt lgkmcnt(1)
	v_pk_add_f32 v[18:19], v[10:11], v[14:15] neg_lo:[0,1] neg_hi:[0,1]
	v_pk_add_f32 v[10:11], v[10:11], v[14:15]
	v_pk_mul_f32 v[22:23], v[20:21], v[18:19] op_sel_hi:[0,1]
	v_pk_fma_f32 v[24:25], v[18:19], v[4:5], v[22:23] op_sel:[0,0,1] op_sel_hi:[1,1,0]
	v_pk_fma_f32 v[18:19], v[18:19], v[4:5], v[22:23] op_sel:[0,0,1] op_sel_hi:[1,0,0] neg_lo:[0,0,1] neg_hi:[0,0,1]
	v_add_f32_e32 v8, v8, v8
	v_mov_b32_e32 v25, v19
	s_waitcnt lgkmcnt(0)
	v_pk_add_f32 v[18:19], v[12:13], v[16:17] neg_lo:[0,1] neg_hi:[0,1]
	v_pk_add_f32 v[12:13], v[12:13], v[16:17]
	v_xor_b32_e32 v23, 0x80000000, v18
	v_pk_add_f32 v[14:15], v[10:11], v[12:13]
	v_pk_add_f32 v[10:11], v[10:11], v[12:13] neg_lo:[0,1] neg_hi:[0,1]
	v_mov_b32_e32 v22, v19
	v_pk_mul_f32 v[18:19], v[20:21], v[18:19] op_sel_hi:[0,1]
	v_pk_mul_f32 v[12:13], v[8:9], v[10:11] op_sel_hi:[0,1]
	v_pk_add_f32 v[6:7], v[6:7], v[6:7] op_sel:[0,1] op_sel_hi:[0,1] neg_lo:[0,1] neg_hi:[0,1]
	v_pk_fma_f32 v[4:5], v[4:5], v[22:23], v[18:19] op_sel_hi:[0,1,1] neg_lo:[0,0,1] neg_hi:[0,0,1]
	ds_write_b64 v21, v[14:15]
	v_pk_fma_f32 v[14:15], v[6:7], v[10:11], v[12:13] op_sel:[0,0,1] op_sel_hi:[1,1,0] neg_lo:[0,0,1] neg_hi:[0,0,1]
	v_pk_fma_f32 v[10:11], v[6:7], v[10:11], v[12:13] op_sel:[0,0,1] op_sel_hi:[1,1,0]
	s_nop 0
	v_mov_b32_e32 v15, v11
	v_pk_add_f32 v[10:11], v[24:25], v[4:5]
	v_pk_add_f32 v[4:5], v[24:25], v[4:5] neg_lo:[0,1] neg_hi:[0,1]
	ds_write_b64 v26, v[14:15]
	v_pk_mul_f32 v[8:9], v[8:9], v[4:5] op_sel_hi:[0,1]
	ds_write_b64 v27, v[10:11]
	v_pk_fma_f32 v[10:11], v[6:7], v[4:5], v[8:9] op_sel:[0,0,1] op_sel_hi:[1,1,0] neg_lo:[0,0,1] neg_hi:[0,0,1]
	v_pk_fma_f32 v[4:5], v[6:7], v[4:5], v[8:9] op_sel:[0,0,1] op_sel_hi:[1,1,0]
	s_nop 0
	v_mov_b32_e32 v11, v5
	ds_write_b64 v28, v[10:11]
	s_cbranch_scc1 .LBB0_489
	s_branch .Lfft_done_1
; DI float sin_t(float turns) { return __builtin_amdgcn_sinf(__builtin_amdgcn_fractf(turns)); }
; DI float cos_t(float turns) { return __builtin_amdgcn_cosf(__builtin_amdgcn_fractf(turns)); }
; DI float2 cmul(float2 a, float2 b) { return make_float2(a.x * b.x - a.y * b.y, a.x * b.y + a.y * b.x); }
; template <int N, bool INV>
; DI void fft_lds(float2* s) {
;     ...
; #pragma unroll 4
;       for (int it = 0; it < N / 4 / NT; ++it) {
;         int idx = tid + it * NT;
;         int j = idx & (q - 1), blk = idx >> lq;
;         int p0 = blk * 4 * q + j;
;         float f = (float)j * inv4q;
;         float2 t1 = make_float2(cos_t(f), -sin_t(f));
;         float2 t2 = cmul(t1, t1);
;         float2 x0 = s[phys(p0)], x1 = s[phys(p0 + q)], x2 = s[phys(p0 + 2 * q)], x3 = s[phys(p0 + 3 * q)];
;         float2 a0 = make_float2(x0.x + x2.x, x0.y + x2.y);
;         float2 a2 = cmul(make_float2(x0.x - x2.x, x0.y - x2.y), t1);
;         float2 a1 = make_float2(x1.x + x3.x, x1.y + x3.y);
;         float2 d3 = make_float2(x1.x - x3.x, x1.y - x3.y);
;         float2 a3 = cmul(make_float2(d3.y, -d3.x), t1);
;         s[phys(p0)] = make_float2(a0.x + a1.x, a0.y + a1.y);
;         s[phys(p0 + q)] = cmul(make_float2(a0.x - a1.x, a0.y - a1.y), t2);
;         s[phys(p0 + 2 * q)] = make_float2(a2.x + a3.x, a2.y + a3.y);
;         s[phys(p0 + 3 * q)] = cmul(make_float2(a2.x - a3.x, a2.y - a3.y), t2);
;       }
.Lfft_fast_1:
	v_add_u32_e32 v21, s11, v2
	v_ashrrev_i32_e32 v4, s0, v21
	v_and_b32_e32 v9, s10, v21
	v_lshlrev_b32_e32 v10, 2, v4
	v_lshl_add_u32 v11, v10, s0, v9
	v_ashrrev_i32_e32 v12, 4, v11
	v_add_lshl_u32 v26, v12, v11, 3
	v_cvt_f32_u32_e32 v4, v9
	v_mul_f32_e32 v4, v3, v4
	v_fract_f32_e32 v5, v4
	v_add_u32_e32 v27, s32, v26
	v_add_u32_e32 v28, s32, v27
	v_add_u32_e32 v29, s32, v28
	v_cos_f32_e32 v4, v5
	v_sin_f32_e32 v5, v5
	ds_read_b64 v[10:11], v26
	ds_read_b64 v[12:13], v27
	ds_read_b64 v[14:15], v28
	ds_read_b64 v[16:17], v29
	v_mov_b32_e32 v20, v5
	v_mul_f32_e64 v8, v4, -v5
	v_pk_mul_f32 v[6:7], v[4:5], v[4:5]
	s_waitcnt lgkmcnt(1)
	v_pk_add_f32 v[18:19], v[10:11], v[14:15] neg_lo:[0,1] neg_hi:[0,1]
	v_pk_add_f32 v[10:11], v[10:11], v[14:15]
	v_pk_mul_f32 v[22:23], v[20:21], v[18:19] op_sel_hi:[0,1]
	v_pk_fma_f32 v[24:25], v[18:19], v[4:5], v[22:23] op_sel:[0,0,1] op_sel_hi:[1,1,0]
	v_pk_fma_f32 v[18:19], v[18:19], v[4:5], v[22:23] op_sel:[0,0,1] op_sel_hi:[1,0,0] neg_lo:[0,0,1] neg_hi:[0,0,1]
	v_add_f32_e32 v8, v8, v8
	v_mov_b32_e32 v25, v19
	s_waitcnt lgkmcnt(0)
	v_pk_add_f32 v[18:19], v[12:13], v[16:17] neg_lo:[0,1] neg_hi:[0,1]
	v_pk_add_f32 v[12:13], v[12:13], v[16:17]
	v_xor_b32_e32 v23, 0x80000000, v18
	v_pk_add_f32 v[14:15], v[10:11], v[12:13]
	v_pk_add_f32 v[10:11], v[10:11], v[12:13] neg_lo:[0,1] neg_hi:[0,1]
	v_mov_b32_e32 v22, v19
	v_pk_mul_f32 v[18:19], v[20:21], v[18:19] op_sel_hi:[0,1]
	v_pk_mul_f32 v[12:13], v[8:9], v[10:11] op_sel_hi:[0,1]
	v_pk_add_f32 v[6:7], v[6:7], v[6:7] op_sel:[0,1] op_sel_hi:[0,1] neg_lo:[0,1] neg_hi:[0,1]
	v_pk_fma_f32 v[4:5], v[4:5], v[22:23], v[18:19] op_sel_hi:[0,1,1] neg_lo:[0,0,1] neg_hi:[0,0,1]
	ds_write_b64 v26, v[14:15]
	v_pk_fma_f32 v[14:15], v[6:7], v[10:11], v[12:13] op_sel:[0,0,1] op_sel_hi:[1,1,0] neg_lo:[0,0,1] neg_hi:[0,0,1]
	v_pk_fma_f32 v[10:11], v[6:7], v[10:11], v[12:13] op_sel:[0,0,1] op_sel_hi:[1,1,0]
	s_addk_i32 s11, 0x800
	v_mov_b32_e32 v15, v11
	v_pk_add_f32 v[10:11], v[24:25], v[4:5]
	v_pk_add_f32 v[4:5], v[24:25], v[4:5] neg_lo:[0,1] neg_hi:[0,1]
	ds_write_b64 v27, v[14:15]
	v_pk_mul_f32 v[8:9], v[8:9], v[4:5] op_sel_hi:[0,1]
	ds_write_b64 v28, v[10:11]
	v_pk_fma_f32 v[10:11], v[6:7], v[4:5], v[8:9] op_sel:[0,0,1] op_sel_hi:[1,1,0] neg_lo:[0,0,1] neg_hi:[0,0,1]
	v_pk_fma_f32 v[4:5], v[6:7], v[4:5], v[8:9] op_sel:[0,0,1] op_sel_hi:[1,1,0]
	s_cmpk_lg_i32 s11, 0x1000
	v_add_u32_e32 v4, 0x200, v21
	v_mov_b32_e32 v11, v5
	v_and_b32_e32 v9, s10, v4
	v_ashrrev_i32_e32 v4, s0, v4
	ds_write_b64 v29, v[10:11]
	v_lshlrev_b32_e32 v10, 2, v4
	v_lshl_add_u32 v11, v10, s0, v9
	v_ashrrev_i32_e32 v12, 4, v11
	v_add_lshl_u32 v26, v12, v11, 3
	v_cvt_f32_u32_e32 v4, v9
	v_mul_f32_e32 v4, v3, v4
	v_fract_f32_e32 v5, v4
	v_add_u32_e32 v27, s32, v26
	v_add_u32_e32 v28, s32, v27
	v_add_u32_e32 v29, s32, v28
	v_cos_f32_e32 v4, v5
	v_sin_f32_e32 v5, v5
	ds_read_b64 v[10:11], v26
	ds_read_b64 v[12:13], v27
	ds_read_b64 v[14:15], v28
	ds_read_b64 v[16:17], v29
	v_mov_b32_e32 v20, v5
	v_mul_f32_e64 v8, v4, -v5
	v_pk_mul_f32 v[6:7], v[4:5], v[4:5]
	s_waitcnt lgkmcnt(1)
	v_pk_add_f32 v[18:19], v[10:11], v[14:15] neg_lo:[0,1] neg_hi:[0,1]
	v_pk_add_f32 v[10:11], v[10:11], v[14:15]
	v_pk_mul_f32 v[22:23], v[20:21], v[18:19] op_sel_hi:[0,1]
	v_pk_fma_f32 v[24:25], v[18:19], v[4:5], v[22:23] op_sel:[0,0,1] op_sel_hi:[1,1,0]
	v_pk_fma_f32 v[18:19], v[18:19], v[4:5], v[22:23] op_sel:[0,0,1] op_sel_hi:[1,0,0] neg_lo:[0,0,1] neg_hi:[0,0,1]
	v_add_f32_e32 v8, v8, v8
	v_mov_b32_e32 v25, v19
	s_waitcnt lgkmcnt(0)
	v_pk_add_f32 v[18:19], v[12:13], v[16:17] neg_lo:[0,1] neg_hi:[0,1]
	v_pk_add_f32 v[12:13], v[12:13], v[16:17]
	v_xor_b32_e32 v23, 0x80000000, v18
	v_pk_add_f32 v[14:15], v[10:11], v[12:13]
	v_pk_add_f32 v[10:11], v[10:11], v[12:13] neg_lo:[0,1] neg_hi:[0,1]
	v_mov_b32_e32 v22, v19
	v_pk_mul_f32 v[18:19], v[20:21], v[18:19] op_sel_hi:[0,1]
	v_pk_mul_f32 v[12:13], v[8:9], v[10:11] op_sel_hi:[0,1]
	v_pk_add_f32 v[6:7], v[6:7], v[6:7] op_sel:[0,1] op_sel_hi:[0,1] neg_lo:[0,1] neg_hi:[0,1]
	v_pk_fma_f32 v[4:5], v[4:5], v[22:23], v[18:19] op_sel_hi:[0,1,1] neg_lo:[0,0,1] neg_hi:[0,0,1]
	ds_write_b64 v26, v[14:15]
	v_pk_fma_f32 v[14:15], v[6:7], v[10:11], v[12:13] op_sel:[0,0,1] op_sel_hi:[1,1,0] neg_lo:[0,0,1] neg_hi:[0,0,1]
	v_pk_fma_f32 v[10:11], v[6:7], v[10:11], v[12:13] op_sel:[0,0,1] op_sel_hi:[1,1,0]
	s_nop 0
	v_mov_b32_e32 v15, v11
	v_pk_add_f32 v[10:11], v[24:25], v[4:5]
	v_pk_add_f32 v[4:5], v[24:25], v[4:5] neg_lo:[0,1] neg_hi:[0,1]
	ds_write_b64 v27, v[14:15]
	v_pk_mul_f32 v[8:9], v[8:9], v[4:5] op_sel_hi:[0,1]
	ds_write_b64 v28, v[10:11]
	v_pk_fma_f32 v[10:11], v[6:7], v[4:5], v[8:9] op_sel:[0,0,1] op_sel_hi:[1,1,0] neg_lo:[0,0,1] neg_hi:[0,0,1]
	v_pk_fma_f32 v[4:5], v[6:7], v[4:5], v[8:9] op_sel:[0,0,1] op_sel_hi:[1,1,0]
	s_nop 0
	v_add_u32_e32 v4, 0x400, v21
	v_mov_b32_e32 v11, v5
	v_and_b32_e32 v9, s10, v4
	v_ashrrev_i32_e32 v4, s0, v4
	ds_write_b64 v29, v[10:11]
	v_lshlrev_b32_e32 v10, 2, v4
	v_lshl_add_u32 v11, v10, s0, v9
	v_ashrrev_i32_e32 v12, 4, v11
	v_add_lshl_u32 v26, v12, v11, 3
	v_cvt_f32_u32_e32 v4, v9
	v_mul_f32_e32 v4, v3, v4
	v_fract_f32_e32 v5, v4
	v_add_u32_e32 v27, s32, v26
	v_add_u32_e32 v28, s32, v27
	v_add_u32_e32 v29, s32, v28
	v_cos_f32_e32 v4, v5
	v_sin_f32_e32 v5, v5
	ds_read_b64 v[10:11], v26
	ds_read_b64 v[12:13], v27
	ds_read_b64 v[14:15], v28
	ds_read_b64 v[16:17], v29
	v_mov_b32_e32 v20, v5
	v_mul_f32_e64 v8, v4, -v5
	v_pk_mul_f32 v[6:7], v[4:5], v[4:5]
	s_waitcnt lgkmcnt(1)
; DI float sin_t(float turns) { return __builtin_amdgcn_sinf(__builtin_amdgcn_fractf(turns)); }
; DI float cos_t(float turns) { return __builtin_amdgcn_cosf(__builtin_amdgcn_fractf(turns)); }
; DI float2 cmul(float2 a, float2 b) { return make_float2(a.x * b.x - a.y * b.y, a.x * b.y + a.y * b.x); }
; template <int N, bool INV>
; DI void fft_lds(float2* s) {
;     ...
;     for (int lq = (LG & 1) ? LG - 3 : LG - 2; lq >= 0; lq -= 2) {
;       const int q = 1 << lq;
;       __syncthreads();
;       const float inv4q = 1.0f / (float)(4 * q);
; #pragma unroll 4
;       for (int it = 0; it < N / 4 / NT; ++it) {
;         int idx = tid + it * NT;
;         int j = idx & (q - 1), blk = idx >> lq;
;         int p0 = blk * 4 * q + j;
;         float f = (float)j * inv4q;
;         float2 t1 = make_float2(cos_t(f), -sin_t(f));
;         float2 t2 = cmul(t1, t1);
;         float2 x0 = s[phys(p0)], x1 = s[phys(p0 + q)], x2 = s[phys(p0 + 2 * q)], x3 = s[phys(p0 + 3 * q)];
;         float2 a0 = make_float2(x0.x + x2.x, x0.y + x2.y);
;         float2 a2 = cmul(make_float2(x0.x - x2.x, x0.y - x2.y), t1);
;         float2 a1 = make_float2(x1.x + x3.x, x1.y + x3.y);
;         float2 d3 = make_float2(x1.x - x3.x, x1.y - x3.y);
;         float2 a3 = cmul(make_float2(d3.y, -d3.x), t1);
;         s[phys(p0)] = make_float2(a0.x + a1.x, a0.y + a1.y);
;         s[phys(p0 + q)] = cmul(make_float2(a0.x - a1.x, a0.y - a1.y), t2);
;         s[phys(p0 + 2 * q)] = make_float2(a2.x + a3.x, a2.y + a3.y);
;         s[phys(p0 + 3 * q)] = cmul(make_float2(a2.x - a3.x, a2.y - a3.y), t2);
;       }
; DI void hyena_lat_item(const P& p, int l, int c, int bp, unsigned char* lds) {
;     ...
;     fft_lds<16384, false>(s);
;     const float2* H = (const float2*)(p.ws + O_SPEC) + ((size_t)(l * 2 + ord) * 256 + c) * 16384;
; #pragma unroll 8
;     for (int i = tid; i < 16384; i += NT) { s[phys(i)] = cmul(s[phys(i)], H[i]); }
	v_pk_add_f32 v[18:19], v[10:11], v[14:15] neg_lo:[0,1] neg_hi:[0,1]
	v_pk_add_f32 v[10:11], v[10:11], v[14:15]
	v_pk_mul_f32 v[22:23], v[20:21], v[18:19] op_sel_hi:[0,1]
	v_pk_fma_f32 v[24:25], v[18:19], v[4:5], v[22:23] op_sel:[0,0,1] op_sel_hi:[1,1,0]
	v_pk_fma_f32 v[18:19], v[18:19], v[4:5], v[22:23] op_sel:[0,0,1] op_sel_hi:[1,0,0] neg_lo:[0,0,1] neg_hi:[0,0,1]
	v_add_f32_e32 v8, v8, v8
	v_mov_b32_e32 v25, v19
	s_waitcnt lgkmcnt(0)
	v_pk_add_f32 v[18:19], v[12:13], v[16:17] neg_lo:[0,1] neg_hi:[0,1]
	v_pk_add_f32 v[12:13], v[12:13], v[16:17]
	v_xor_b32_e32 v23, 0x80000000, v18
	v_pk_add_f32 v[14:15], v[10:11], v[12:13]
	v_pk_add_f32 v[10:11], v[10:11], v[12:13] neg_lo:[0,1] neg_hi:[0,1]
	v_mov_b32_e32 v22, v19
	v_pk_mul_f32 v[18:19], v[20:21], v[18:19] op_sel_hi:[0,1]
	v_pk_mul_f32 v[12:13], v[8:9], v[10:11] op_sel_hi:[0,1]
	v_pk_add_f32 v[6:7], v[6:7], v[6:7] op_sel:[0,1] op_sel_hi:[0,1] neg_lo:[0,1] neg_hi:[0,1]
	v_pk_fma_f32 v[4:5], v[4:5], v[22:23], v[18:19] op_sel_hi:[0,1,1] neg_lo:[0,0,1] neg_hi:[0,0,1]
	ds_write_b64 v26, v[14:15]
	v_pk_fma_f32 v[14:15], v[6:7], v[10:11], v[12:13] op_sel:[0,0,1] op_sel_hi:[1,1,0] neg_lo:[0,0,1] neg_hi:[0,0,1]
	v_pk_fma_f32 v[10:11], v[6:7], v[10:11], v[12:13] op_sel:[0,0,1] op_sel_hi:[1,1,0]
	s_nop 0
	v_mov_b32_e32 v15, v11
	v_pk_add_f32 v[10:11], v[24:25], v[4:5]
	v_pk_add_f32 v[4:5], v[24:25], v[4:5] neg_lo:[0,1] neg_hi:[0,1]
	ds_write_b64 v27, v[14:15]
	v_pk_mul_f32 v[8:9], v[8:9], v[4:5] op_sel_hi:[0,1]
	ds_write_b64 v28, v[10:11]
	v_pk_fma_f32 v[10:11], v[6:7], v[4:5], v[8:9] op_sel:[0,0,1] op_sel_hi:[1,1,0] neg_lo:[0,0,1] neg_hi:[0,0,1]
	v_pk_fma_f32 v[4:5], v[6:7], v[4:5], v[8:9] op_sel:[0,0,1] op_sel_hi:[1,1,0]
	s_nop 0
	v_add_u32_e32 v4, 0x600, v21
	v_mov_b32_e32 v11, v5
	v_and_b32_e32 v9, s10, v4
	v_ashrrev_i32_e32 v4, s0, v4
	ds_write_b64 v29, v[10:11]
	v_lshlrev_b32_e32 v10, 2, v4
	v_lshl_add_u32 v11, v10, s0, v9
	v_ashrrev_i32_e32 v12, 4, v11
	v_add_lshl_u32 v21, v12, v11, 3
	v_cvt_f32_u32_e32 v4, v9
	v_mul_f32_e32 v4, v3, v4
	v_fract_f32_e32 v5, v4
	v_add_u32_e32 v26, s32, v21
	v_add_u32_e32 v27, s32, v26
	v_add_u32_e32 v28, s32, v27
	v_cos_f32_e32 v4, v5
	v_sin_f32_e32 v5, v5
	ds_read_b64 v[10:11], v21
	ds_read_b64 v[12:13], v26
	ds_read_b64 v[14:15], v27
	ds_read_b64 v[16:17], v28
	v_mov_b32_e32 v20, v5
	v_mul_f32_e64 v8, v4, -v5
	v_pk_mul_f32 v[6:7], v[4:5], v[4:5]
	s_waitcnt lgkmcnt(1)
	v_pk_add_f32 v[18:19], v[10:11], v[14:15] neg_lo:[0,1] neg_hi:[0,1]
	v_pk_add_f32 v[10:11], v[10:11], v[14:15]
	v_pk_mul_f32 v[22:23], v[20:21], v[18:19] op_sel_hi:[0,1]
	v_pk_fma_f32 v[24:25], v[18:19], v[4:5], v[22:23] op_sel:[0,0,1] op_sel_hi:[1,1,0]
	v_pk_fma_f32 v[18:19], v[18:19], v[4:5], v[22:23] op_sel:[0,0,1] op_sel_hi:[1,0,0] neg_lo:[0,0,1] neg_hi:[0,0,1]
	v_add_f32_e32 v8, v8, v8
	v_mov_b32_e32 v25, v19
	s_waitcnt lgkmcnt(0)
	v_pk_add_f32 v[18:19], v[12:13], v[16:17] neg_lo:[0,1] neg_hi:[0,1]
	v_pk_add_f32 v[12:13], v[12:13], v[16:17]
	v_xor_b32_e32 v23, 0x80000000, v18
	v_pk_add_f32 v[14:15], v[10:11], v[12:13]
	v_pk_add_f32 v[10:11], v[10:11], v[12:13] neg_lo:[0,1] neg_hi:[0,1]
	v_mov_b32_e32 v22, v19
	v_pk_mul_f32 v[18:19], v[20:21], v[18:19] op_sel_hi:[0,1]
	v_pk_mul_f32 v[12:13], v[8:9], v[10:11] op_sel_hi:[0,1]
	v_pk_add_f32 v[6:7], v[6:7], v[6:7] op_sel:[0,1] op_sel_hi:[0,1] neg_lo:[0,1] neg_hi:[0,1]
	v_pk_fma_f32 v[4:5], v[4:5], v[22:23], v[18:19] op_sel_hi:[0,1,1] neg_lo:[0,0,1] neg_hi:[0,0,1]
	ds_write_b64 v21, v[14:15]
	v_pk_fma_f32 v[14:15], v[6:7], v[10:11], v[12:13] op_sel:[0,0,1] op_sel_hi:[1,1,0] neg_lo:[0,0,1] neg_hi:[0,0,1]
	v_pk_fma_f32 v[10:11], v[6:7], v[10:11], v[12:13] op_sel:[0,0,1] op_sel_hi:[1,1,0]
	s_nop 0
	v_mov_b32_e32 v15, v11
	v_pk_add_f32 v[10:11], v[24:25], v[4:5]
	v_pk_add_f32 v[4:5], v[24:25], v[4:5] neg_lo:[0,1] neg_hi:[0,1]
	ds_write_b64 v26, v[14:15]
	v_pk_mul_f32 v[8:9], v[8:9], v[4:5] op_sel_hi:[0,1]
	ds_write_b64 v27, v[10:11]
	v_pk_fma_f32 v[10:11], v[6:7], v[4:5], v[8:9] op_sel:[0,0,1] op_sel_hi:[1,1,0] neg_lo:[0,0,1] neg_hi:[0,0,1]
	v_pk_fma_f32 v[4:5], v[6:7], v[4:5], v[8:9] op_sel:[0,0,1] op_sel_hi:[1,1,0]
	s_nop 0
	v_mov_b32_e32 v11, v5
	ds_write_b64 v28, v[10:11]
	s_cbranch_scc1 .Lfft_fast_1
.Lfft_done_1:
	s_add_i32 s1, s0, -2
	s_cmp_lg_u32 s0, 0
	s_mov_b32 s0, s1
	s_cbranch_scc1 .LBB0_488
	s_waitcnt lgkmcnt(0)
	s_barrier
	s_and_saveexec_b64 s[0:1], s[4:5]
	s_cbranch_execz .LBB0_499
	v_add_u32_e32 v4, 0x1ff, v70
	v_and_b32_e32 v2, 0xe00, v4
	s_movk_i32 s4, 0xe00
	v_cmp_ne_u32_e32 vcc, s4, v2
	s_and_saveexec_b64 s[4:5], vcc
	s_cbranch_execz .LBB0_496
	v_lshrrev_b32_e32 v2, 9, v4
	s_lshl_b64 s[10:11], s[6:7], 17
	v_readlane_b32 s12, v251, 0
	v_add_u32_e32 v2, 1, v2
	s_add_u32 s10, s12, s10
	v_readlane_b32 s12, v251, 1
	v_and_b32_e32 v6, 7, v2
	v_ashrrev_i32_e32 v53, 31, v52
	s_addc_u32 s11, s12, s11
	v_lshl_add_u64 v[2:3], v[52:53], 3, s[10:11]
	v_add_u32_e32 v5, 0, v50
	v_sub_u32_e32 v6, 0, v6
	s_mov_b64 s[10:11], 0
	s_mov_b64 s[12:13], 0x1000
